# v23 + dilated-merge epilogue: the 3 later partial-output load pairs per query tile issued together with the first pair (fresh regs, counted vmcnt waits), same arithmetic
# baseline (speedup 1.0000x reference)
; #define LAS __attribute__((address_space(3)))
; template <int NK, int NT, int KSTR, class BM>
; __device__ __forceinline__ void attn_step(LAS const unsigned char* Kl, LAS const unsigned char* Vl, int kb, const bf16x8 (&q)[NT][NK], f32x4 (&o)[NT][4], float (&mrun)[NT], float (&lrun)[NT], int lane, const BM& bm) {
;     ...
;         float p0[4], p1[4]; float ps = 0.f;
; #pragma unroll
;         for (int j = 0; j < 4; ++j) { p0[j] = __builtin_amdgcn_exp2f(s0[t][j]); p1[j] = __builtin_amdgcn_exp2f(s1[t][j]); ps += p0[j] + p1[j]; }
;         lrun[t] += ps;
;         u32x4 w; w.x = pk2(p0[0], p0[1]); w.y = pk2(p0[2], p0[3]); w.z = pk2(p1[0], p1[1]); w.w = pk2(p1[2], p1[3]);
;         pb[t] = __builtin_bit_cast(bf16x8, w);
;     }
;     LAS const unsigned char* vp = Vl + (kb + 4 * g + (i >> 2)) * S64 + (i & 3) * 8;
; #pragma unroll
;     for (int db = 0; db < 4; ++db) {
;         const s16x4 lo = vtr(vp + db * 32), hi = vtr(vp + 16 * S64 + db * 32);
;         const bf16x8 va = {lo[0], lo[1], lo[2], lo[3], hi[0], hi[1], hi[2], hi[3]};
; #pragma unroll
;         for (int t = 0; t < NT; ++t) o[t][db] = __builtin_amdgcn_mfma_f32_16x16x32_bf16(va, pb[t], o[t][db], 0, 0, 0);
;     }
; __global__ void __launch_bounds__(NTHR, 2) fwd_megakernel(Params P) {
;     ...
;                 for (int t = 0; t < 2; ++t) {
;                     const int tq = ((256 * mb + 128 * t + w16 + i) << dl) + r;
;                     float lt = lr[t][0]; lt += __shfl_xor(lt, 16); lt += __shfl_xor(lt, 32);
;                     const float inv = 1.0f / lt;
;                     const size_t row = (size_t)b * SEQ + tq;
;                     const float l2v = mr[t][0] + __log2f(lt);
;                     if (!do_merge) {
;                         bf16_t* op = PART + ((size_t)p * MTOK + row) * 512 + 64 * h + 4 * g4;
; #pragma unroll
;                         for (int db = 0; db < 4; ++db) { u32x2 w; w.x = pk2(o[t][0][db][0] * inv, o[t][0][db][1] * inv); w.y = pk2(o[t][0][db][2] * inv, o[t][0][db][3] * inv); *(u32x2*)(op + 16 * db) = w; }
;                         if (g4 == 0) lse[((size_t)p * MTOK + row) * 8 + h] = l2v;
;                     } else {
;                         const float l0 = lse[((size_t)0 * MTOK + row) * 8 + h], l1 = lse[((size_t)1 * MTOK + row) * 8 + h];
;                         const float mxl = fmaxf(l2v, fmaxf(l0, l1));
.LBB0_767:
	v_add_f32_e32 v75, v138, v80
	v_add_f32_e32 v75, 0, v75
	v_add_f32_e32 v76, v139, v81
	v_add_f32_e32 v75, v76, v75
	v_add_f32_e32 v76, v82, v137
	v_add_f32_e32 v75, v76, v75
	v_add_f32_e32 v76, v83, v140
	v_add_f32_e32 v75, v76, v75
	v_exp_f32_e32 v77, v68
	v_exp_f32_e32 v79, v72
	v_exp_f32_e32 v76, v69
	v_exp_f32_e32 v78, v73
	v_add_f32_e32 v116, v136, v75
	s_sub_i32 s5, 4, s36
	v_pk_mov_b32 v[72:73], v[76:77], v[76:77] op_sel:[1,0]
	v_pk_add_f32 v[68:69], v[78:79], v[76:77]
	v_pk_mov_b32 v[76:77], v[78:79], v[78:79] op_sel:[1,0]
	v_add_f32_e32 v69, 0, v69
	v_add_f32_e32 v75, v68, v69
	v_exp_f32_e32 v69, v14
	v_exp_f32_e32 v79, v70
	v_exp_f32_e32 v68, v15
	v_exp_f32_e32 v78, v71
	s_lshr_b32 s8, s44, s5
	s_lshl_b32 s5, s20, 8
	v_pk_mov_b32 v[70:71], v[68:69], v[68:69] op_sel:[1,0]
	v_pk_add_f32 v[14:15], v[78:79], v[68:69]
	v_pk_mov_b32 v[78:79], v[78:79], v[78:79] op_sel:[1,0]
	v_add_f32_e32 v15, v15, v75
	v_add_f32_e32 v14, v14, v15
	v_add_f32_e32 v15, v74, v14
	v_cvt_pk_bf16_f32 v68, v72, v73
	v_cvt_pk_bf16_f32 v69, v70, v71
	v_cvt_pk_bf16_f32 v70, v76, v77
	v_cvt_pk_bf16_f32 v71, v78, v79
	ds_read_b64_tr_b16 v[74:75], v185 offset:2560
	ds_read_b64_tr_b16 v[78:79], v185 offset:2592
	ds_read_b64_tr_b16 v[72:73], v184 offset:64000
	ds_read_b64_tr_b16 v[76:77], v184 offset:64032
	s_waitcnt lgkmcnt(1)
	v_mfma_f32_16x16x32_bf16 v[80:83], v[72:75], v[68:71], v[100:103]
	ds_read_b64_tr_b16 v[72:73], v184 offset:64064
	ds_read_b64_tr_b16 v[74:75], v185 offset:2624
	s_nop 0
	ds_read_b64_tr_b16 v[100:101], v184 offset:64096
	ds_read_b64_tr_b16 v[102:103], v185 offset:2656
	s_bfe_u32 s4, s20, 0x30008
	s_waitcnt lgkmcnt(2)
	v_mfma_f32_16x16x32_bf16 v[72:75], v[72:75], v[68:71], v[108:111]
	s_and_b32 s20, s5, 0xf000
	s_nop 1
	v_add_u32_e32 v108, s37, v194
	v_lshlrev_b32_e32 v14, s36, v108
	v_mfma_f32_16x16x32_bf16 v[76:79], v[76:79], v[68:71], v[104:107]
	s_mov_b64 s[12:13], 0x10000
	s_mov_b32 s5, s21
	s_waitcnt lgkmcnt(0)
	v_mfma_f32_16x16x32_bf16 v[68:71], v[100:103], v[68:71], v[112:115]
	v_add_u32_e32 v100, s8, v14
	ds_bpermute_b32 v14, v196, v116
	s_waitcnt lgkmcnt(0)
	v_add_f32_e32 v14, v116, v14
	ds_bpermute_b32 v101, v197, v14
	s_waitcnt lgkmcnt(0)
	v_add_f32_e32 v14, v14, v101
	v_div_scale_f32 v101, s[6:7], v14, v14, 1.0
	v_rcp_f32_e32 v102, v101
	s_lshl_b32 s6, s4, 2
	s_mov_b32 s7, s21
	s_lshl_b32 s4, s4, 7
	v_fma_f32 v103, -v101, v102, 1.0
	v_fmac_f32_e32 v102, v103, v102
	v_div_scale_f32 v103, vcc, 1.0, v14, 1.0
	v_mul_f32_e32 v104, v103, v102
	v_fma_f32 v105, -v101, v104, v103
	v_fmac_f32_e32 v104, v105, v102
	v_fma_f32 v101, -v101, v104, v103
	v_div_fmas_f32 v101, v101, v102, v104
	v_div_fixup_f32 v109, v101, v14, 1.0
	v_ashrrev_i32_e32 v101, 31, v100
	v_lshl_add_u64 v[100:101], v[100:101], 0, s[20:21]
	v_log_f32_e32 v14, v14
	v_lshlrev_b64 v[102:103], 5, v[100:101]
	v_lshl_add_u64 v[102:103], s[90:91], 0, v[102:103]
	v_lshl_add_u64 v[102:103], v[102:103], 0, s[6:7]
	v_lshl_add_u64 v[104:105], v[100:101], 0, s[12:13]
	v_add_f32_e32 v12, v12, v14
	global_load_dword v14, v[102:103], off
	v_lshlrev_b64 v[102:103], 5, v[104:105]
	v_lshl_add_u64 v[102:103], s[90:91], 0, v[102:103]
	v_lshl_add_u64 v[102:103], v[102:103], 0, s[6:7]
	global_load_dword v102, v[102:103], off
	v_lshlrev_b64 v[104:105], 10, v[104:105]
	s_waitcnt vmcnt(0)
	v_max3_f32 v103, v12, v14, v102
	v_sub_f32_e32 v14, v14, v103
	v_exp_f32_e32 v107, v14
	v_sub_f32_e32 v14, v102, v103
	v_exp_f32_e32 v106, v14
	v_sub_f32_e32 v12, v12, v103
	v_exp_f32_e32 v12, v12
	v_add_f32_e32 v14, v107, v106
	v_add_f32_e32 v14, v12, v14
	v_div_scale_f32 v102, s[10:11], v14, v14, 1.0
	v_rcp_f32_e32 v103, v102
	v_readlane_b32 s10, v252, 50
	v_readlane_b32 s11, v252, 51
	v_fma_f32 v110, -v102, v103, 1.0
	v_fmac_f32_e32 v103, v110, v103
	v_div_scale_f32 v110, vcc, 1.0, v14, 1.0
	v_mul_f32_e32 v111, v110, v103
	v_fma_f32 v112, -v102, v111, v110
	v_fmac_f32_e32 v111, v112, v103
	v_fma_f32 v102, -v102, v111, v110
	v_div_fmas_f32 v102, v102, v103, v111
	v_div_fixup_f32 v110, v102, v14, 1.0
	v_lshlrev_b64 v[102:103], 10, v[100:101]
	v_mul_f32_e32 v14, v109, v110
	v_lshl_add_u64 v[102:103], s[10:11], 0, v[102:103]
	v_mul_f32_e32 v14, v12, v14
	v_lshl_add_u64 v[102:103], v[102:103], 0, s[4:5]
	v_lshlrev_b32_e32 v12, 1, v154
	v_lshl_add_u64 v[104:105], s[10:11], 0, v[104:105]
	v_lshl_add_u64 v[102:103], v[102:103], 0, v[12:13]
	v_lshl_add_u64 v[104:105], v[104:105], 0, s[4:5]
	v_lshl_add_u64 v[104:105], v[104:105], 0, v[12:13]
	global_load_dwordx2 v[112:113], v[102:103], off
	global_load_dwordx2 v[114:115], v[104:105], off
	global_load_dwordx2 v[240:241], v[102:103], off offset:32
	global_load_dwordx2 v[242:243], v[104:105], off offset:32
	global_load_dwordx2 v[244:245], v[102:103], off offset:64
	global_load_dwordx2 v[246:247], v[104:105], off offset:64
	global_load_dwordx2 v[248:249], v[102:103], off offset:96
	global_load_dwordx2 v[250:251], v[104:105], off offset:96
	v_pk_mul_f32 v[106:107], v[106:107], v[110:111] op_sel_hi:[1,0]
	v_lshlrev_b64 v[100:101], 11, v[100:101]
	v_lshl_add_u64 v[100:101], s[74:75], 0, v[100:101]
	v_lshl_add_u64 v[100:101], v[100:101], 0, s[4:5]
	v_lshl_add_u64 v[100:101], v[100:101], 0, v[12:13]
	s_waitcnt vmcnt(7)
	v_lshlrev_b32_e32 v116, 16, v112
	s_waitcnt vmcnt(6)
; __device__ __forceinline__ unsigned pk2(float lo, float hi) { f32x2 v = {lo, hi}; bf16x2_t b = __builtin_convertvector(v, bf16x2_t); return __builtin_bit_cast(unsigned, b); }
; __global__ void __launch_bounds__(NTHR, 2) fwd_megakernel(Params P) {
;     ...
;                 for (int t = 0; t < 2; ++t) {
;                     const int tq = ((256 * mb + 128 * t + w16 + i) << dl) + r;
;                     float lt = lr[t][0]; lt += __shfl_xor(lt, 16); lt += __shfl_xor(lt, 32);
;                     const float inv = 1.0f / lt;
;                     const size_t row = (size_t)b * SEQ + tq;
;                     const float l2v = mr[t][0] + __log2f(lt);
;                     if (!do_merge) {
;                         bf16_t* op = PART + ((size_t)p * MTOK + row) * 512 + 64 * h + 4 * g4;
; #pragma unroll
;                         for (int db = 0; db < 4; ++db) { u32x2 w; w.x = pk2(o[t][0][db][0] * inv, o[t][0][db][1] * inv); w.y = pk2(o[t][0][db][2] * inv, o[t][0][db][3] * inv); *(u32x2*)(op + 16 * db) = w; }
;                         if (g4 == 0) lse[((size_t)p * MTOK + row) * 8 + h] = l2v;
;                     } else {
;                         const float l0 = lse[((size_t)0 * MTOK + row) * 8 + h], l1 = lse[((size_t)1 * MTOK + row) * 8 + h];
;                         const float mxl = fmaxf(l2v, fmaxf(l0, l1));
;                         float w0 = __builtin_amdgcn_exp2f(l0 - mxl), w1 = __builtin_amdgcn_exp2f(l1 - mxl), w2 = __builtin_amdgcn_exp2f(l2v - mxl);
;                         const float iw = 1.0f / (w0 + w1 + w2); w0 *= iw; w1 *= iw; w2 *= iw * inv;
;                         const bf16_t* pa = PART + ((size_t)0 * MTOK + row) * 512 + 64 * h + 4 * g4; const bf16_t* pb1 = PART + ((size_t)1 * MTOK + row) * 512 + 64 * h + 4 * g4;
;                         bf16_t* op = OB + row * DM + 256 + 64 * h + 4 * g4;
; #pragma unroll
;                         for (int db = 0; db < 4; ++db) { const u32x2 a = *(const u32x2*)(pa + 16 * db), c1 = *(const u32x2*)(pb1 + 16 * db);
;                             u32x2 w;
;                             w.x = pk2(w0 * bflo(a.x) + w1 * bflo(c1.x) + w2 * o[t][0][db][0], w0 * bfhi(a.x) + w1 * bfhi(c1.x) + w2 * o[t][0][db][1]);
;                             w.y = pk2(w0 * bflo(a.y) + w1 * bflo(c1.y) + w2 * o[t][0][db][2], w0 * bfhi(a.y) + w1 * bfhi(c1.y) + w2 * o[t][0][db][3]);
;                             *(u32x2*)(op + 16 * db) = w; }
	v_and_b32_e32 v117, 0xffff0000, v114
	v_lshlrev_b32_e32 v110, 16, v114
	v_and_b32_e32 v111, 0xffff0000, v112
	v_pk_mul_f32 v[116:117], v[106:107], v[116:117] op_sel:[1,0] op_sel_hi:[0,1]
	v_pk_fma_f32 v[110:111], v[106:107], v[110:111], v[116:117]
	v_lshlrev_b32_e32 v112, 16, v113
	v_pk_fma_f32 v[96:97], v[96:97], v[14:15], v[110:111] op_sel_hi:[1,0,1]
	v_and_b32_e32 v111, 0xffff0000, v113
	v_and_b32_e32 v113, 0xffff0000, v115
	v_lshlrev_b32_e32 v110, 16, v115
	v_pk_mul_f32 v[112:113], v[106:107], v[112:113] op_sel:[1,0] op_sel_hi:[0,1]
	v_pk_fma_f32 v[110:111], v[106:107], v[110:111], v[112:113]
	v_cvt_pk_bf16_f32 v96, v96, v97
	v_pk_fma_f32 v[98:99], v[98:99], v[14:15], v[110:111] op_sel_hi:[1,0,1]
	s_nop 0
	v_cvt_pk_bf16_f32 v97, v98, v99
	global_store_dwordx2 v[100:101], v[96:97], off offset:512
	s_waitcnt vmcnt(6)
	v_lshlrev_b32_e32 v112, 16, v240
	s_waitcnt vmcnt(5)
	v_and_b32_e32 v113, 0xffff0000, v242
	v_lshlrev_b32_e32 v110, 16, v242
	v_and_b32_e32 v111, 0xffff0000, v240
	v_pk_mul_f32 v[112:113], v[106:107], v[112:113] op_sel:[1,0] op_sel_hi:[0,1]
	v_pk_fma_f32 v[110:111], v[106:107], v[110:111], v[112:113]
	v_lshlrev_b32_e32 v96, 16, v241
	v_pk_fma_f32 v[92:93], v[92:93], v[14:15], v[110:111] op_sel_hi:[1,0,1]
	v_and_b32_e32 v111, 0xffff0000, v241
	v_and_b32_e32 v97, 0xffff0000, v243
	v_lshlrev_b32_e32 v110, 16, v243
	v_pk_mul_f32 v[96:97], v[106:107], v[96:97] op_sel:[1,0] op_sel_hi:[0,1]
	v_pk_fma_f32 v[96:97], v[106:107], v[110:111], v[96:97]
	v_cvt_pk_bf16_f32 v92, v92, v93
	v_pk_fma_f32 v[94:95], v[94:95], v[14:15], v[96:97] op_sel_hi:[1,0,1]
	s_nop 0
	v_cvt_pk_bf16_f32 v93, v94, v95
	global_store_dwordx2 v[100:101], v[92:93], off offset:544
	s_waitcnt vmcnt(5)
	v_lshlrev_b32_e32 v98, 16, v244
	s_waitcnt vmcnt(4)
	v_and_b32_e32 v99, 0xffff0000, v246
	v_lshlrev_b32_e32 v96, 16, v246
	v_and_b32_e32 v97, 0xffff0000, v244
	v_pk_mul_f32 v[98:99], v[106:107], v[98:99] op_sel:[1,0] op_sel_hi:[0,1]
	v_pk_fma_f32 v[96:97], v[106:107], v[96:97], v[98:99]
	v_lshlrev_b32_e32 v92, 16, v245
	v_pk_fma_f32 v[88:89], v[88:89], v[14:15], v[96:97] op_sel_hi:[1,0,1]
	v_and_b32_e32 v97, 0xffff0000, v245
	v_and_b32_e32 v93, 0xffff0000, v247
	v_lshlrev_b32_e32 v96, 16, v247
	v_pk_mul_f32 v[92:93], v[106:107], v[92:93] op_sel:[1,0] op_sel_hi:[0,1]
	v_pk_fma_f32 v[92:93], v[106:107], v[96:97], v[92:93]
	v_cvt_pk_bf16_f32 v88, v88, v89
	v_pk_fma_f32 v[90:91], v[90:91], v[14:15], v[92:93] op_sel_hi:[1,0,1]
	s_nop 0
	v_cvt_pk_bf16_f32 v89, v90, v91
	global_store_dwordx2 v[100:101], v[88:89], off offset:576
	s_waitcnt vmcnt(4)
	v_lshlrev_b32_e32 v94, 16, v248
	s_waitcnt vmcnt(3)
	v_and_b32_e32 v95, 0xffff0000, v250
	v_lshlrev_b32_e32 v92, 16, v250
	v_and_b32_e32 v93, 0xffff0000, v248
	v_pk_mul_f32 v[94:95], v[106:107], v[94:95] op_sel:[1,0] op_sel_hi:[0,1]
	v_pk_fma_f32 v[92:93], v[106:107], v[92:93], v[94:95]
	v_lshlrev_b32_e32 v88, 16, v249
	v_pk_fma_f32 v[84:85], v[84:85], v[14:15], v[92:93] op_sel_hi:[1,0,1]
	v_and_b32_e32 v93, 0xffff0000, v249
	v_and_b32_e32 v89, 0xffff0000, v251
	v_lshlrev_b32_e32 v92, 16, v251
	v_pk_mul_f32 v[88:89], v[106:107], v[88:89] op_sel:[1,0] op_sel_hi:[0,1]
	v_pk_fma_f32 v[88:89], v[106:107], v[92:93], v[88:89]
	v_cvt_pk_bf16_f32 v84, v84, v85
	v_pk_fma_f32 v[86:87], v[86:87], v[14:15], v[88:89] op_sel_hi:[1,0,1]
	v_add_u32_e32 v14, 0x80, v108
	v_cvt_pk_bf16_f32 v85, v86, v87
	global_store_dwordx2 v[100:101], v[84:85], off offset:608
	ds_bpermute_b32 v84, v196, v15
	v_lshlrev_b32_e32 v14, s36, v14
	v_add_u32_e32 v14, s8, v14
	s_waitcnt lgkmcnt(0)
	v_add_f32_e32 v15, v15, v84
	ds_bpermute_b32 v84, v197, v15
	s_waitcnt lgkmcnt(0)
	v_add_f32_e32 v86, v15, v84
	v_div_scale_f32 v15, s[8:9], v86, v86, 1.0
	v_rcp_f32_e32 v84, v15
	s_nop 0
	v_fma_f32 v85, -v15, v84, 1.0
	v_fmac_f32_e32 v84, v85, v84
	v_div_scale_f32 v85, vcc, 1.0, v86, 1.0
	v_mul_f32_e32 v87, v85, v84
	v_fma_f32 v88, -v15, v87, v85
	v_fmac_f32_e32 v87, v88, v84
	v_fma_f32 v15, -v15, v87, v85
	v_div_fmas_f32 v15, v15, v84, v87
	v_div_fixup_f32 v88, v15, v86, 1.0
	v_ashrrev_i32_e32 v15, 31, v14
	v_lshl_add_u64 v[84:85], v[14:15], 0, s[20:21]
	v_log_f32_e32 v14, v86
	v_lshl_add_u64 v[86:87], v[84:85], 0, s[12:13]
	s_mov_b32 s20, s18
	v_add_f32_e32 v89, v166, v14
	v_lshlrev_b64 v[14:15], 5, v[84:85]
	v_lshl_add_u64 v[14:15], s[90:91], 0, v[14:15]
	v_lshl_add_u64 v[14:15], v[14:15], 0, s[6:7]
	global_load_dword v90, v[14:15], off
	v_lshlrev_b64 v[14:15], 5, v[86:87]
	v_lshl_add_u64 v[14:15], s[90:91], 0, v[14:15]
	v_lshl_add_u64 v[14:15], v[14:15], 0, s[6:7]
	global_load_dword v14, v[14:15], off
	v_lshlrev_b64 v[86:87], 10, v[86:87]
	v_lshl_add_u64 v[86:87], s[10:11], 0, v[86:87]
	v_lshl_add_u64 v[86:87], v[86:87], 0, s[4:5]
	s_waitcnt vmcnt(0)
; __device__ __forceinline__ unsigned pk2(float lo, float hi) { f32x2 v = {lo, hi}; bf16x2_t b = __builtin_convertvector(v, bf16x2_t); return __builtin_bit_cast(unsigned, b); }
; __device__ __forceinline__ float bflo(unsigned u) { return __uint_as_float(u << 16); }
; __device__ __forceinline__ float bfhi(unsigned u) { return __uint_as_float(u & 0xffff0000u); }
; __global__ void __launch_bounds__(NTHR, 2) fwd_megakernel(Params P) {
;     ...
;                         const float l0 = lse[((size_t)0 * MTOK + row) * 8 + h], l1 = lse[((size_t)1 * MTOK + row) * 8 + h];
;                         const float mxl = fmaxf(l2v, fmaxf(l0, l1));
;                         float w0 = __builtin_amdgcn_exp2f(l0 - mxl), w1 = __builtin_amdgcn_exp2f(l1 - mxl), w2 = __builtin_amdgcn_exp2f(l2v - mxl);
;                         const float iw = 1.0f / (w0 + w1 + w2); w0 *= iw; w1 *= iw; w2 *= iw * inv;
;                         const bf16_t* pa = PART + ((size_t)0 * MTOK + row) * 512 + 64 * h + 4 * g4; const bf16_t* pb1 = PART + ((size_t)1 * MTOK + row) * 512 + 64 * h + 4 * g4;
;                         bf16_t* op = OB + row * DM + 256 + 64 * h + 4 * g4;
; #pragma unroll
;                         for (int db = 0; db < 4; ++db) { const u32x2 a = *(const u32x2*)(pa + 16 * db), c1 = *(const u32x2*)(pb1 + 16 * db);
;                             u32x2 w;
;                             w.x = pk2(w0 * bflo(a.x) + w1 * bflo(c1.x) + w2 * o[t][0][db][0], w0 * bfhi(a.x) + w1 * bfhi(c1.x) + w2 * o[t][0][db][1]);
;                             w.y = pk2(w0 * bflo(a.y) + w1 * bflo(c1.y) + w2 * o[t][0][db][2], w0 * bfhi(a.y) + w1 * bfhi(c1.y) + w2 * o[t][0][db][3]);
;                             *(u32x2*)(op + 16 * db) = w; }
;                     }
;                 }
;                 __syncthreads();
	v_max3_f32 v15, v89, v90, v14
	v_sub_f32_e32 v90, v90, v15
	v_sub_f32_e32 v14, v14, v15
	v_exp_f32_e32 v93, v90
	v_exp_f32_e32 v92, v14
	v_sub_f32_e32 v14, v89, v15
	v_exp_f32_e32 v14, v14
	v_add_f32_e32 v15, v93, v92
	v_add_f32_e32 v15, v14, v15
	v_div_scale_f32 v89, s[6:7], v15, v15, 1.0
	v_rcp_f32_e32 v90, v89
	s_nop 0
	v_fma_f32 v91, -v89, v90, 1.0
	v_fmac_f32_e32 v90, v91, v90
	v_div_scale_f32 v91, vcc, 1.0, v15, 1.0
	v_mul_f32_e32 v94, v91, v90
	v_fma_f32 v95, -v89, v94, v91
	v_fmac_f32_e32 v94, v95, v90
	v_fma_f32 v89, -v89, v94, v91
	v_div_fmas_f32 v89, v89, v90, v94
	v_div_fixup_f32 v94, v89, v15, 1.0
	v_mul_f32_e32 v15, v88, v94
	v_lshlrev_b64 v[88:89], 10, v[84:85]
	v_lshl_add_u64 v[88:89], s[10:11], 0, v[88:89]
	v_lshl_add_u64 v[88:89], v[88:89], 0, s[4:5]
	v_lshl_add_u64 v[90:91], v[88:89], 0, v[12:13]
	v_lshl_add_u64 v[88:89], v[86:87], 0, v[12:13]
	global_load_dwordx2 v[96:97], v[90:91], off
	global_load_dwordx2 v[98:99], v[88:89], off
	global_load_dwordx2 v[240:241], v[90:91], off offset:32
	global_load_dwordx2 v[242:243], v[88:89], off offset:32
	global_load_dwordx2 v[244:245], v[90:91], off offset:64
	global_load_dwordx2 v[246:247], v[88:89], off offset:64
	global_load_dwordx2 v[248:249], v[90:91], off offset:96
	global_load_dwordx2 v[250:251], v[88:89], off offset:96
	v_pk_mul_f32 v[86:87], v[92:93], v[94:95] op_sel_hi:[1,0]
	v_mul_f32_e32 v14, v14, v15
	v_lshlrev_b64 v[84:85], 11, v[84:85]
	v_lshl_add_u64 v[84:85], s[74:75], 0, v[84:85]
	v_lshl_add_u64 v[84:85], v[84:85], 0, s[4:5]
	v_lshl_add_u64 v[84:85], v[84:85], 0, v[12:13]
	s_andn2_b64 vcc, exec, s[0:1]
	s_waitcnt vmcnt(7)
	v_lshlrev_b32_e32 v94, 16, v96
	s_waitcnt vmcnt(6)
	v_and_b32_e32 v95, 0xffff0000, v98
	v_lshlrev_b32_e32 v92, 16, v98
	v_and_b32_e32 v93, 0xffff0000, v96
	v_pk_mul_f32 v[94:95], v[86:87], v[94:95] op_sel:[1,0] op_sel_hi:[0,1]
	v_pk_fma_f32 v[92:93], v[86:87], v[92:93], v[94:95]
	v_lshlrev_b32_e32 v94, 16, v97
	v_and_b32_e32 v95, 0xffff0000, v99
	v_pk_fma_f32 v[80:81], v[80:81], v[14:15], v[92:93] op_sel_hi:[1,0,1]
	v_lshlrev_b32_e32 v92, 16, v99
	v_and_b32_e32 v93, 0xffff0000, v97
	v_pk_mul_f32 v[94:95], v[86:87], v[94:95] op_sel:[1,0] op_sel_hi:[0,1]
	v_pk_fma_f32 v[92:93], v[86:87], v[92:93], v[94:95]
	v_cvt_pk_bf16_f32 v80, v80, v81
	v_pk_fma_f32 v[82:83], v[82:83], v[14:15], v[92:93] op_sel_hi:[1,0,1]
	s_nop 0
	v_cvt_pk_bf16_f32 v81, v82, v83
	global_store_dwordx2 v[84:85], v[80:81], off offset:512
	s_waitcnt vmcnt(6)
	v_lshlrev_b32_e32 v94, 16, v240
	s_waitcnt vmcnt(5)
	v_and_b32_e32 v95, 0xffff0000, v242
	v_lshlrev_b32_e32 v92, 16, v242
	v_and_b32_e32 v93, 0xffff0000, v240
	v_pk_mul_f32 v[94:95], v[86:87], v[94:95] op_sel:[1,0] op_sel_hi:[0,1]
	v_pk_fma_f32 v[92:93], v[86:87], v[92:93], v[94:95]
	v_lshlrev_b32_e32 v80, 16, v241
	v_pk_fma_f32 v[76:77], v[76:77], v[14:15], v[92:93] op_sel_hi:[1,0,1]
	v_and_b32_e32 v93, 0xffff0000, v241
	v_and_b32_e32 v81, 0xffff0000, v243
	v_lshlrev_b32_e32 v92, 16, v243
	v_pk_mul_f32 v[80:81], v[86:87], v[80:81] op_sel:[1,0] op_sel_hi:[0,1]
	v_pk_fma_f32 v[80:81], v[86:87], v[92:93], v[80:81]
	v_cvt_pk_bf16_f32 v76, v76, v77
	v_pk_fma_f32 v[78:79], v[78:79], v[14:15], v[80:81] op_sel_hi:[1,0,1]
	s_nop 0
	v_cvt_pk_bf16_f32 v77, v78, v79
	global_store_dwordx2 v[84:85], v[76:77], off offset:544
	s_waitcnt vmcnt(5)
	v_lshlrev_b32_e32 v82, 16, v244
	s_waitcnt vmcnt(4)
	v_and_b32_e32 v83, 0xffff0000, v246
	v_lshlrev_b32_e32 v80, 16, v246
	v_and_b32_e32 v81, 0xffff0000, v244
	v_pk_mul_f32 v[82:83], v[86:87], v[82:83] op_sel:[1,0] op_sel_hi:[0,1]
	v_pk_fma_f32 v[80:81], v[86:87], v[80:81], v[82:83]
	v_lshlrev_b32_e32 v76, 16, v245
	v_pk_fma_f32 v[72:73], v[72:73], v[14:15], v[80:81] op_sel_hi:[1,0,1]
	v_and_b32_e32 v81, 0xffff0000, v245
	v_and_b32_e32 v77, 0xffff0000, v247
	v_lshlrev_b32_e32 v80, 16, v247
	v_pk_mul_f32 v[76:77], v[86:87], v[76:77] op_sel:[1,0] op_sel_hi:[0,1]
	v_pk_fma_f32 v[76:77], v[86:87], v[80:81], v[76:77]
	v_cvt_pk_bf16_f32 v72, v72, v73
	v_pk_fma_f32 v[74:75], v[74:75], v[14:15], v[76:77] op_sel_hi:[1,0,1]
	v_mov_b64_e32 v[82:83], v[54:55]
	v_cvt_pk_bf16_f32 v73, v74, v75
	global_store_dwordx2 v[84:85], v[72:73], off offset:576
	v_mov_b64_e32 v[80:81], v[52:53]
	s_waitcnt vmcnt(4)
	v_lshlrev_b32_e32 v78, 16, v248
	s_waitcnt vmcnt(3)
	v_and_b32_e32 v79, 0xffff0000, v250
	v_lshlrev_b32_e32 v76, 16, v250
	v_and_b32_e32 v77, 0xffff0000, v248
	v_pk_mul_f32 v[78:79], v[86:87], v[78:79] op_sel:[1,0] op_sel_hi:[0,1]
	v_pk_fma_f32 v[76:77], v[86:87], v[76:77], v[78:79]
	v_lshlrev_b32_e32 v72, 16, v249
	v_pk_fma_f32 v[68:69], v[68:69], v[14:15], v[76:77] op_sel_hi:[1,0,1]
	v_and_b32_e32 v77, 0xffff0000, v249
	v_and_b32_e32 v73, 0xffff0000, v251
	v_lshlrev_b32_e32 v76, 16, v251
	v_pk_mul_f32 v[72:73], v[86:87], v[72:73] op_sel:[1,0] op_sel_hi:[0,1]
	v_pk_fma_f32 v[72:73], v[86:87], v[76:77], v[72:73]
	v_cvt_pk_bf16_f32 v68, v68, v69
	v_pk_fma_f32 v[14:15], v[70:71], v[14:15], v[72:73] op_sel_hi:[1,0,1]
	v_mov_b64_e32 v[78:79], v[58:59]
	v_cvt_pk_bf16_f32 v69, v14, v15
	global_store_dwordx2 v[84:85], v[68:69], off offset:608
	v_mov_b64_e32 v[74:75], v[66:67]
	v_mov_b64_e32 v[70:71], v[62:63]
	v_mov_b64_e32 v[76:77], v[56:57]
	v_mov_b64_e32 v[72:73], v[64:65]
	v_mov_b64_e32 v[68:69], v[60:61]
	s_barrier
	s_cbranch_vccz .LBB0_851
